# P2/P9: in the peeled first k-iteration of every unit after the first, the first three waits no longer wait for the previous epilogue's store acks (exact in-order counts)
# speedup vs baseline: 1.0122x; 1.0006x over previous
;     __device__ __forceinline__ bool next(int i, Unit& u) const { return decode(i * G + c, u); }
; #define PG8_STAGE(bufoff, gbase, voff) do { _Pragma("unroll") for (int _i = 0; _i < 2; ++_i) \
;         __builtin_amdgcn_global_load_lds((const unsigned*)((const char*)(gbase) + (voff)[_i]), (LAS unsigned*)(lds + (bufoff) + ldsw + _i * 8192), 16, 0, 0); } while (0)
; #define PG8_LDA(dst, b, h) do { _Pragma("unroll") for (int m = 0; m < 4; ++m) _Pragma("unroll") for (int k = 0; k < 2; ++k) dst[m][k] = *(const LAS bf16x8*)(lds + PG8_SA(b, h) + aoff + m * 2048 + k * 1024); } while (0)
; #define PG8_LDB(dst, b, h) do { _Pragma("unroll") for (int n = 0; n < 2; ++n) _Pragma("unroll") for (int k = 0; k < 2; ++k) dst[n][k] = *(const LAS bf16x8*)(lds + PG8_SB(b, h) + boff + n * 2048 + k * 1024); } while (0)
; #define PG8_WAIT_V(n) asm volatile("s_waitcnt vmcnt(" #n ")" ::: "memory")
; #define PG8_WAIT_L(n) asm volatile("s_waitcnt lgkmcnt(" #n ")" ::: "memory")
; #define PG8_BAR __builtin_amdgcn_s_barrier()
; #define PG8_SCHED __builtin_amdgcn_sched_barrier(0)
; template <class Epi, class Sched, bool DEFER>
; __device__ __forceinline__ void gemm_fast_core(LAS unsigned char* lds, const GemmP g, const Sched& S, const Epi& E, f32x4 (&acc)[2][2][4][2], Unit& cur) {
;     ...
;         const bool has_next = S.next(ui + 1, nxt);
;         const char* nA = has_next ? (const char*)g.aptr(nxt) : cA; const char* nB = has_next ? (const char*)g.bptr(nxt) : cB;
;         for (int t = 0; t < nt; t += 2) {
;             const bool last = (t == nt - 2);
;             const char* a1 = cA + (size_t)(t + 1) * kstep;
;             const char* a2 = last ? nA : cA + (size_t)(t + 2) * kstep; const char* b2 = last ? nB : cB + (size_t)(t + 2) * kstep;
;             const char* a3 = a2 + kstep; const char* b3 = b2 + kstep;
;             PG8_LDB(B0, 0, 0); PG8_LDB(B1, 0, 1); PG8_SCHED; PG8_LDA(At, 0, 0); PG8_STAGE(PG8_SA(1, 1), a1 + hstepA, voffA);
;             PG8_WAIT_V(8); PG8_WAIT_L(0); PG8_BAR; PG8_MMA(0, 0, At, B0); PG8_MMA(0, 1, At, B1); PG8_BAR; PG8_SCHED;
;             PG8_LDA(At, 0, 1); PG8_STAGE(PG8_SB(0, 0), b2, voffB); PG8_STAGE(PG8_SB(0, 1), b2 + hstepB, voffB); PG8_STAGE(PG8_SA(0, 0), a2, voffA);
;             PG8_WAIT_V(8); PG8_WAIT_L(0); PG8_BAR; PG8_MMA(1, 0, At, B0); PG8_MMA(1, 1, At, B1); PG8_BAR; PG8_SCHED;
.LBB0_235:
	s_ashr_i32 s25, s24, 31
	s_lshl_b64 s[30:31], s[24:25], 20
	s_add_u32 s30, s90, s30
	s_addc_u32 s31, s91, s31
	s_and_b64 s[34:35], s[28:29], exec
	s_cselect_b32 s3, s31, s37
	s_cselect_b32 s25, s30, s36
	s_ashr_i32 s23, s22, 31
	s_lshl_b64 s[34:35], s[22:23], 20
	s_add_u32 s34, s10, s34
	s_addc_u32 s35, s11, s35
	s_and_b64 s[40:41], s[28:29], exec
	s_cselect_b32 s23, s35, s39
	s_cselect_b32 s27, s34, s38
	s_add_u32 s36, s36, 0x80080
	s_addc_u32 s37, s37, 0
	s_add_u32 s33, s38, 0x100
	s_addc_u32 s42, s39, 0
	s_mov_b32 s43, -2
	.p2align 6
	ds_read_b128 v[136:139], v143
	ds_read_b128 v[146:149], v143 offset:1024
	ds_read_b128 v[150:153], v143 offset:2048
	ds_read_b128 v[154:157], v143 offset:3072
	ds_read_b128 v[158:161], v144
	ds_read_b128 v[162:165], v144 offset:1024
	ds_read_b128 v[166:169], v144 offset:2048
	ds_read_b128 v[170:173], v144 offset:3072
	s_add_u32 s38, s36, 0xfff80080
	s_addc_u32 s39, s37, -1
	s_cmp_eq_u32 s43, 28
	s_cselect_b32 s41, s3, s39
	s_cselect_b32 s40, s25, s38
	s_cselect_b32 s39, s23, s42
	s_cselect_b32 s38, s27, s33
	v_lshl_add_u64 v[186:187], s[36:37], 0, v[132:133]
	s_add_i32 m0, s48, 0xc000
	ds_read_b128 v[174:177], v145
	ds_read_b128 v[178:181], v145 offset:1024
	ds_read_b128 v[182:185], v145 offset:2048
	ds_read_b128 v[192:195], v145 offset:3072
	ds_read_b128 v[196:199], v145 offset:4096
	ds_read_b128 v[200:203], v145 offset:5120
	ds_read_b128 v[204:207], v145 offset:6144
	ds_read_b128 v[208:211], v145 offset:7168
	global_load_lds_dwordx4 v[186:187], off
	v_lshl_add_u64 v[186:187], s[36:37], 0, v[134:135]
	s_add_i32 m0, s48, 0xe000
	s_nop 0
	global_load_lds_dwordx4 v[186:187], off
	s_cmp_eq_u32 s73, 1
	s_cbranch_scc1 .Lpw_p2_0_strict
	s_branch .Lpw_p2_0_done
.Lpw_p2_0_strict:
	s_waitcnt vmcnt(8)
.Lpw_p2_0_done:
	s_waitcnt lgkmcnt(0)
	s_barrier
	s_setprio 1
	s_waitcnt lgkmcnt(0)
	v_mfma_f32_16x16x32_bf16 v[124:127], v[136:139], v[174:177], 0
	v_mfma_f32_16x16x32_bf16 v[120:123], v[150:153], v[174:177], 0
	v_mfma_f32_16x16x32_bf16 v[108:111], v[136:139], v[182:185], 0
	v_mfma_f32_16x16x32_bf16 v[104:107], v[150:153], v[182:185], 0
	v_mfma_f32_16x16x32_bf16 v[92:95], v[136:139], v[196:199], 0
	v_mfma_f32_16x16x32_bf16 v[88:91], v[150:153], v[196:199], 0
	v_mfma_f32_16x16x32_bf16 v[76:79], v[136:139], v[204:207], 0
	v_mfma_f32_16x16x32_bf16 v[72:75], v[150:153], v[204:207], 0
	v_mfma_f32_16x16x32_bf16 v[124:127], v[146:149], v[178:181], v[124:127]
	v_mfma_f32_16x16x32_bf16 v[120:123], v[154:157], v[178:181], v[120:123]
	v_mfma_f32_16x16x32_bf16 v[108:111], v[146:149], v[192:195], v[108:111]
	v_mfma_f32_16x16x32_bf16 v[104:107], v[154:157], v[192:195], v[104:107]
	v_mfma_f32_16x16x32_bf16 v[92:95], v[146:149], v[200:203], v[92:95]
	v_mfma_f32_16x16x32_bf16 v[88:91], v[154:157], v[200:203], v[88:91]
	v_mfma_f32_16x16x32_bf16 v[76:79], v[146:149], v[208:211], v[76:79]
	v_mfma_f32_16x16x32_bf16 v[72:75], v[154:157], v[208:211], v[72:75]
	s_setprio 0
	s_setprio 1
	v_mfma_f32_16x16x32_bf16 v[116:119], v[158:161], v[174:177], 0
	v_mfma_f32_16x16x32_bf16 v[112:115], v[166:169], v[174:177], 0
	v_mfma_f32_16x16x32_bf16 v[100:103], v[158:161], v[182:185], 0
	v_mfma_f32_16x16x32_bf16 v[96:99], v[166:169], v[182:185], 0
	v_mfma_f32_16x16x32_bf16 v[84:87], v[158:161], v[196:199], 0
	v_mfma_f32_16x16x32_bf16 v[80:83], v[166:169], v[196:199], 0
	v_mfma_f32_16x16x32_bf16 v[68:71], v[158:161], v[204:207], 0
	v_mfma_f32_16x16x32_bf16 v[64:67], v[166:169], v[204:207], 0
	v_mfma_f32_16x16x32_bf16 v[116:119], v[162:165], v[178:181], v[116:119]
	v_mfma_f32_16x16x32_bf16 v[112:115], v[170:173], v[178:181], v[112:115]
	v_mfma_f32_16x16x32_bf16 v[100:103], v[162:165], v[192:195], v[100:103]
	v_mfma_f32_16x16x32_bf16 v[96:99], v[170:173], v[192:195], v[96:99]
	v_mfma_f32_16x16x32_bf16 v[84:87], v[162:165], v[200:203], v[84:87]
	v_mfma_f32_16x16x32_bf16 v[80:83], v[170:173], v[200:203], v[80:83]
	v_mfma_f32_16x16x32_bf16 v[68:71], v[162:165], v[208:211], v[68:71]
	v_mfma_f32_16x16x32_bf16 v[64:67], v[170:173], v[208:211], v[64:67]
	s_setprio 0
	s_barrier
	s_add_i32 s44, s76, s21
	v_lshl_add_u64 v[186:187], s[38:39], 0, v[128:129]
	s_mov_b32 m0, s44
	ds_read_b128 v[174:177], v145 offset:16384
	ds_read_b128 v[178:181], v145 offset:17408
	ds_read_b128 v[182:185], v145 offset:18432
	ds_read_b128 v[192:195], v145 offset:19456
	ds_read_b128 v[196:199], v145 offset:20480
	ds_read_b128 v[200:203], v145 offset:21504
	ds_read_b128 v[204:207], v145 offset:22528
	ds_read_b128 v[208:211], v145 offset:23552
	global_load_lds_dwordx4 v[186:187], off
	s_add_i32 m0, s44, 0x2000
	s_add_u32 s44, s38, 0x80000
	v_lshl_add_u64 v[212:213], s[38:39], 0, v[130:131]
	s_addc_u32 s45, s39, 0
	s_add_i32 s46, s77, s21
	global_load_lds_dwordx4 v[212:213], off
	v_lshl_add_u64 v[214:215], s[44:45], 0, v[128:129]
	s_mov_b32 m0, s46
	v_lshl_add_u64 v[216:217], s[40:41], 0, v[130:131]
	global_load_lds_dwordx4 v[214:215], off
	v_lshl_add_u64 v[214:215], s[44:45], 0, v[130:131]
	s_add_i32 m0, s46, 0x2000
	s_nop 0
	global_load_lds_dwordx4 v[214:215], off
	v_lshl_add_u64 v[214:215], s[40:41], 0, v[128:129]
	s_mov_b32 m0, s48
	s_nop 0
	global_load_lds_dwordx4 v[214:215], off
	s_mov_b32 m0, s49
	s_nop 0
	global_load_lds_dwordx4 v[216:217], off
	s_cmp_eq_u32 s73, 1
	s_cbranch_scc1 .Lpw_p2_1_strict
	s_waitcnt vmcnt(28)
	s_branch .Lpw_p2_1_done

; #define PG8_STAGE(bufoff, gbase, voff) do { _Pragma("unroll") for (int _i = 0; _i < 2; ++_i) \
;         __builtin_amdgcn_global_load_lds((const unsigned*)((const char*)(gbase) + (voff)[_i]), (LAS unsigned*)(lds + (bufoff) + ldsw + _i * 8192), 16, 0, 0); } while (0)
; #define PG8_LDA(dst, b, h) do { _Pragma("unroll") for (int m = 0; m < 4; ++m) _Pragma("unroll") for (int k = 0; k < 2; ++k) dst[m][k] = *(const LAS bf16x8*)(lds + PG8_SA(b, h) + aoff + m * 2048 + k * 1024); } while (0)
; #define PG8_LDB(dst, b, h) do { _Pragma("unroll") for (int n = 0; n < 2; ++n) _Pragma("unroll") for (int k = 0; k < 2; ++k) dst[n][k] = *(const LAS bf16x8*)(lds + PG8_SB(b, h) + boff + n * 2048 + k * 1024); } while (0)
; #define PG8_MMA(ai, bj, At, Bt) do { __builtin_amdgcn_s_setprio(1); _Pragma("unroll") for (int m = 0; m < 4; ++m) _Pragma("unroll") for (int n = 0; n < 2; ++n) _Pragma("unroll") for (int k = 0; k < 2; ++k) \
;         acc[ai][bj][m][n] = __builtin_amdgcn_mfma_f32_16x16x32_bf16(Bt[n][k], At[m][k], acc[ai][bj][m][n], 0, 0, 0); __builtin_amdgcn_s_setprio(0); } while (0)
; #define PG8_WAIT_V(n) asm volatile("s_waitcnt vmcnt(" #n ")" ::: "memory")
; #define PG8_WAIT_L(n) asm volatile("s_waitcnt lgkmcnt(" #n ")" ::: "memory")
; #define PG8_BAR __builtin_amdgcn_s_barrier()
; #define PG8_SCHED __builtin_amdgcn_sched_barrier(0)
; template <class Epi, class Sched, bool DEFER>
; __device__ __forceinline__ void gemm_fast_core(LAS unsigned char* lds, const GemmP g, const Sched& S, const Epi& E, f32x4 (&acc)[2][2][4][2], Unit& cur) {
;     ...
;             PG8_WAIT_V(8); PG8_WAIT_L(0); PG8_BAR; PG8_MMA(0, 0, At, B0); PG8_MMA(0, 1, At, B1); PG8_BAR; PG8_SCHED;
;             PG8_LDA(At, 0, 1); PG8_STAGE(PG8_SB(0, 0), b2, voffB); PG8_STAGE(PG8_SB(0, 1), b2 + hstepB, voffB); PG8_STAGE(PG8_SA(0, 0), a2, voffA);
;             PG8_WAIT_V(8); PG8_WAIT_L(0); PG8_BAR; PG8_MMA(1, 0, At, B0); PG8_MMA(1, 1, At, B1); PG8_BAR; PG8_SCHED;
;             PG8_LDB(B0, 1, 0); PG8_LDB(B1, 1, 1); PG8_SCHED; PG8_LDA(At, 1, 0); PG8_STAGE(PG8_SA(0, 1), a2 + hstepA, voffA);
.Lpw_p2_1_done:
	s_waitcnt lgkmcnt(0)
	s_barrier
	s_setprio 1
	s_waitcnt lgkmcnt(0)
	v_mfma_f32_16x16x32_bf16 v[60:63], v[136:139], v[174:177], 0
	v_mfma_f32_16x16x32_bf16 v[56:59], v[150:153], v[174:177], 0
	v_mfma_f32_16x16x32_bf16 v[44:47], v[136:139], v[182:185], 0
	v_mfma_f32_16x16x32_bf16 v[40:43], v[150:153], v[182:185], 0
	v_mfma_f32_16x16x32_bf16 v[28:31], v[136:139], v[196:199], 0
	v_mfma_f32_16x16x32_bf16 v[24:27], v[150:153], v[196:199], 0
	v_mfma_f32_16x16x32_bf16 v[12:15], v[136:139], v[204:207], 0
	v_mfma_f32_16x16x32_bf16 v[8:11], v[150:153], v[204:207], 0
	v_mfma_f32_16x16x32_bf16 v[60:63], v[146:149], v[178:181], v[60:63]
	v_mfma_f32_16x16x32_bf16 v[56:59], v[154:157], v[178:181], v[56:59]
	v_mfma_f32_16x16x32_bf16 v[44:47], v[146:149], v[192:195], v[44:47]
	v_mfma_f32_16x16x32_bf16 v[40:43], v[154:157], v[192:195], v[40:43]
	v_mfma_f32_16x16x32_bf16 v[28:31], v[146:149], v[200:203], v[28:31]
	v_mfma_f32_16x16x32_bf16 v[24:27], v[154:157], v[200:203], v[24:27]
	v_mfma_f32_16x16x32_bf16 v[12:15], v[146:149], v[208:211], v[12:15]
	v_mfma_f32_16x16x32_bf16 v[8:11], v[154:157], v[208:211], v[8:11]
	s_setprio 0
	s_setprio 1
	v_mfma_f32_16x16x32_bf16 v[52:55], v[158:161], v[174:177], 0
	v_mfma_f32_16x16x32_bf16 v[48:51], v[166:169], v[174:177], 0
	v_mfma_f32_16x16x32_bf16 v[36:39], v[158:161], v[182:185], 0
	v_mfma_f32_16x16x32_bf16 v[32:35], v[166:169], v[182:185], 0
	v_mfma_f32_16x16x32_bf16 v[20:23], v[158:161], v[196:199], 0
	v_mfma_f32_16x16x32_bf16 v[16:19], v[166:169], v[196:199], 0
	v_mfma_f32_16x16x32_bf16 v[4:7], v[158:161], v[204:207], 0
	v_mfma_f32_16x16x32_bf16 v[0:3], v[166:169], v[204:207], 0
	v_mfma_f32_16x16x32_bf16 v[52:55], v[162:165], v[178:181], v[52:55]
	v_mfma_f32_16x16x32_bf16 v[48:51], v[170:173], v[178:181], v[48:51]
	v_mfma_f32_16x16x32_bf16 v[36:39], v[162:165], v[192:195], v[36:39]
	v_mfma_f32_16x16x32_bf16 v[32:35], v[170:173], v[192:195], v[32:35]
	v_mfma_f32_16x16x32_bf16 v[20:23], v[162:165], v[200:203], v[20:23]
	v_mfma_f32_16x16x32_bf16 v[16:19], v[170:173], v[200:203], v[16:19]
	v_mfma_f32_16x16x32_bf16 v[4:7], v[162:165], v[208:211], v[4:7]
	v_mfma_f32_16x16x32_bf16 v[0:3], v[170:173], v[208:211], v[0:3]
	s_setprio 0
	s_barrier
	s_add_i32 s44, 0, 0x18000
	s_add_i32 s45, 0, 0x1c000
	v_add_u32_e32 v154, s44, v141
	v_add_u32_e32 v170, s45, v141
	ds_read_b128 v[136:139], v154
	ds_read_b128 v[146:149], v154 offset:1024
	ds_read_b128 v[150:153], v154 offset:2048
	ds_read_b128 v[154:157], v154 offset:3072
	ds_read_b128 v[158:161], v170
	ds_read_b128 v[162:165], v170 offset:1024
	ds_read_b128 v[166:169], v170 offset:2048
	ds_read_b128 v[170:173], v170 offset:3072
	s_add_u32 s40, s40, 0x80000
	s_addc_u32 s41, s41, 0
	s_mov_b32 m0, s68
	v_lshl_add_u64 v[218:219], s[40:41], 0, v[128:129]
	ds_read_b128 v[174:177], v145 offset:32768
	ds_read_b128 v[178:181], v145 offset:33792
	ds_read_b128 v[182:185], v145 offset:34816
	ds_read_b128 v[192:195], v145 offset:35840
	ds_read_b128 v[196:199], v145 offset:36864
	ds_read_b128 v[200:203], v145 offset:37888
	ds_read_b128 v[204:207], v145 offset:38912
	ds_read_b128 v[208:211], v145 offset:39936
	global_load_lds_dwordx4 v[218:219], off
	v_lshl_add_u64 v[218:219], s[40:41], 0, v[130:131]
	s_mov_b32 m0, s69
	s_nop 0
	global_load_lds_dwordx4 v[218:219], off
	s_cmp_eq_u32 s73, 1
	s_cbranch_scc1 .Lpw_p2_2_strict
	s_waitcnt vmcnt(24)
	s_branch .Lpw_p2_2_done

; #define PG8_STAGE(bufoff, gbase, voff) do { _Pragma("unroll") for (int _i = 0; _i < 2; ++_i) \
;         __builtin_amdgcn_global_load_lds((const unsigned*)((const char*)(gbase) + (voff)[_i]), (LAS unsigned*)(lds + (bufoff) + ldsw + _i * 8192), 16, 0, 0); } while (0)
; #define PG8_LDA(dst, b, h) do { _Pragma("unroll") for (int m = 0; m < 4; ++m) _Pragma("unroll") for (int k = 0; k < 2; ++k) dst[m][k] = *(const LAS bf16x8*)(lds + PG8_SA(b, h) + aoff + m * 2048 + k * 1024); } while (0)
; #define PG8_LDB(dst, b, h) do { _Pragma("unroll") for (int n = 0; n < 2; ++n) _Pragma("unroll") for (int k = 0; k < 2; ++k) dst[n][k] = *(const LAS bf16x8*)(lds + PG8_SB(b, h) + boff + n * 2048 + k * 1024); } while (0)
; #define PG8_MMA(ai, bj, At, Bt) do { __builtin_amdgcn_s_setprio(1); _Pragma("unroll") for (int m = 0; m < 4; ++m) _Pragma("unroll") for (int n = 0; n < 2; ++n) _Pragma("unroll") for (int k = 0; k < 2; ++k) \
;         acc[ai][bj][m][n] = __builtin_amdgcn_mfma_f32_16x16x32_bf16(Bt[n][k], At[m][k], acc[ai][bj][m][n], 0, 0, 0); __builtin_amdgcn_s_setprio(0); } while (0)
; #define PG8_WAIT_V(n) asm volatile("s_waitcnt vmcnt(" #n ")" ::: "memory")
; #define PG8_WAIT_L(n) asm volatile("s_waitcnt lgkmcnt(" #n ")" ::: "memory")
; #define PG8_BAR __builtin_amdgcn_s_barrier()
; #define PG8_SCHED __builtin_amdgcn_sched_barrier(0)
; template <class Epi, class Sched, bool DEFER>
; __device__ __forceinline__ void gemm_fast_core(LAS unsigned char* lds, const GemmP g, const Sched& S, const Epi& E, f32x4 (&acc)[2][2][4][2], Unit& cur) {
;     ...
;             PG8_WAIT_V(8); PG8_WAIT_L(0); PG8_BAR; PG8_MMA(1, 0, At, B0); PG8_MMA(1, 1, At, B1); PG8_BAR; PG8_SCHED;
;             PG8_LDB(B0, 1, 0); PG8_LDB(B1, 1, 1); PG8_SCHED; PG8_LDA(At, 1, 0); PG8_STAGE(PG8_SA(0, 1), a2 + hstepA, voffA);
;             PG8_WAIT_V(8); PG8_WAIT_L(0); PG8_BAR; PG8_MMA(0, 0, At, B0); PG8_MMA(0, 1, At, B1); PG8_BAR; PG8_SCHED;
;             PG8_LDA(At, 1, 1); PG8_STAGE(PG8_SB(1, 0), b3, voffB); PG8_STAGE(PG8_SB(1, 1), b3 + hstepB, voffB); PG8_STAGE(PG8_SA(1, 0), a3, voffA);
;             PG8_WAIT_V(8); PG8_WAIT_L(0); PG8_BAR; PG8_MMA(1, 0, At, B0); PG8_MMA(1, 1, At, B1); PG8_BAR; PG8_SCHED;
.Lpw_p2_2_done:
	s_waitcnt lgkmcnt(0)
	s_barrier
	s_setprio 1
	s_waitcnt lgkmcnt(0)
	v_mfma_f32_16x16x32_bf16 v[124:127], v[136:139], v[174:177], v[124:127]
	v_mfma_f32_16x16x32_bf16 v[120:123], v[150:153], v[174:177], v[120:123]
	v_mfma_f32_16x16x32_bf16 v[108:111], v[136:139], v[182:185], v[108:111]
	v_mfma_f32_16x16x32_bf16 v[104:107], v[150:153], v[182:185], v[104:107]
	v_mfma_f32_16x16x32_bf16 v[92:95], v[136:139], v[196:199], v[92:95]
	v_mfma_f32_16x16x32_bf16 v[88:91], v[150:153], v[196:199], v[88:91]
	v_mfma_f32_16x16x32_bf16 v[76:79], v[136:139], v[204:207], v[76:79]
	v_mfma_f32_16x16x32_bf16 v[72:75], v[150:153], v[204:207], v[72:75]
	v_mfma_f32_16x16x32_bf16 v[124:127], v[146:149], v[178:181], v[124:127]
	v_mfma_f32_16x16x32_bf16 v[120:123], v[154:157], v[178:181], v[120:123]
	v_mfma_f32_16x16x32_bf16 v[108:111], v[146:149], v[192:195], v[108:111]
	v_mfma_f32_16x16x32_bf16 v[104:107], v[154:157], v[192:195], v[104:107]
	v_mfma_f32_16x16x32_bf16 v[92:95], v[146:149], v[200:203], v[92:95]
	v_mfma_f32_16x16x32_bf16 v[88:91], v[154:157], v[200:203], v[88:91]
	v_mfma_f32_16x16x32_bf16 v[76:79], v[146:149], v[208:211], v[76:79]
	v_mfma_f32_16x16x32_bf16 v[72:75], v[154:157], v[208:211], v[72:75]
	s_setprio 0
	s_setprio 1
	v_mfma_f32_16x16x32_bf16 v[116:119], v[158:161], v[174:177], v[116:119]
	v_mfma_f32_16x16x32_bf16 v[112:115], v[166:169], v[174:177], v[112:115]
	v_mfma_f32_16x16x32_bf16 v[100:103], v[158:161], v[182:185], v[100:103]
	v_mfma_f32_16x16x32_bf16 v[96:99], v[166:169], v[182:185], v[96:99]
	v_mfma_f32_16x16x32_bf16 v[84:87], v[158:161], v[196:199], v[84:87]
	v_mfma_f32_16x16x32_bf16 v[80:83], v[166:169], v[196:199], v[80:83]
	v_mfma_f32_16x16x32_bf16 v[68:71], v[158:161], v[204:207], v[68:71]
	v_mfma_f32_16x16x32_bf16 v[64:67], v[166:169], v[204:207], v[64:67]
	v_mfma_f32_16x16x32_bf16 v[116:119], v[162:165], v[178:181], v[116:119]
	v_mfma_f32_16x16x32_bf16 v[112:115], v[170:173], v[178:181], v[112:115]
	v_mfma_f32_16x16x32_bf16 v[100:103], v[162:165], v[192:195], v[100:103]
	v_mfma_f32_16x16x32_bf16 v[96:99], v[170:173], v[192:195], v[96:99]
	v_mfma_f32_16x16x32_bf16 v[84:87], v[162:165], v[200:203], v[84:87]
	v_mfma_f32_16x16x32_bf16 v[80:83], v[170:173], v[200:203], v[80:83]
	v_mfma_f32_16x16x32_bf16 v[68:71], v[162:165], v[208:211], v[68:71]
	v_mfma_f32_16x16x32_bf16 v[64:67], v[170:173], v[208:211], v[64:67]
	s_setprio 0
	s_barrier
	s_add_i32 s40, s44, s21
	v_lshl_add_u64 v[186:187], v[186:187], 0, s[16:17]
	s_mov_b32 m0, s40
	ds_read_b128 v[174:177], v145 offset:49152
	ds_read_b128 v[178:181], v145 offset:50176
	ds_read_b128 v[182:185], v145 offset:51200
	ds_read_b128 v[192:195], v145 offset:52224
	ds_read_b128 v[196:199], v145 offset:53248
	ds_read_b128 v[200:203], v145 offset:54272
	ds_read_b128 v[204:207], v145 offset:55296
	ds_read_b128 v[208:211], v145 offset:56320
	global_load_lds_dwordx4 v[186:187], off
	s_add_i32 m0, s40, 0x2000
	s_add_u32 s38, s38, 0x80080
	v_lshl_add_u64 v[186:187], v[212:213], 0, s[16:17]
	s_addc_u32 s39, s39, 0
	s_add_i32 s40, s45, s21
	global_load_lds_dwordx4 v[186:187], off
	v_lshl_add_u64 v[186:187], s[38:39], 0, v[128:129]
	s_mov_b32 m0, s40
	s_nop 0
	global_load_lds_dwordx4 v[186:187], off
	v_lshl_add_u64 v[186:187], s[38:39], 0, v[130:131]
	s_add_i32 m0, s40, 0x2000
	s_nop 0
	global_load_lds_dwordx4 v[186:187], off
	v_lshl_add_u64 v[186:187], v[214:215], 0, s[16:17]
	s_mov_b32 m0, s74
	s_nop 0
	global_load_lds_dwordx4 v[186:187], off
	v_lshl_add_u64 v[186:187], v[216:217], 0, s[16:17]
	s_mov_b32 m0, s75
	s_nop 0
	global_load_lds_dwordx4 v[186:187], off
	s_waitcnt vmcnt(8)
	s_waitcnt lgkmcnt(0)
	s_barrier
	s_setprio 1
	s_waitcnt lgkmcnt(0)
	v_mfma_f32_16x16x32_bf16 v[60:63], v[136:139], v[174:177], v[60:63]
	v_mfma_f32_16x16x32_bf16 v[56:59], v[150:153], v[174:177], v[56:59]
	v_mfma_f32_16x16x32_bf16 v[44:47], v[136:139], v[182:185], v[44:47]
	v_mfma_f32_16x16x32_bf16 v[40:43], v[150:153], v[182:185], v[40:43]
	v_mfma_f32_16x16x32_bf16 v[28:31], v[136:139], v[196:199], v[28:31]
	v_mfma_f32_16x16x32_bf16 v[24:27], v[150:153], v[196:199], v[24:27]
	v_mfma_f32_16x16x32_bf16 v[12:15], v[136:139], v[204:207], v[12:15]
	v_mfma_f32_16x16x32_bf16 v[8:11], v[150:153], v[204:207], v[8:11]
	v_mfma_f32_16x16x32_bf16 v[60:63], v[146:149], v[178:181], v[60:63]
	v_mfma_f32_16x16x32_bf16 v[56:59], v[154:157], v[178:181], v[56:59]
	v_mfma_f32_16x16x32_bf16 v[44:47], v[146:149], v[192:195], v[44:47]
	v_mfma_f32_16x16x32_bf16 v[40:43], v[154:157], v[192:195], v[40:43]
	v_mfma_f32_16x16x32_bf16 v[28:31], v[146:149], v[200:203], v[28:31]
	v_mfma_f32_16x16x32_bf16 v[24:27], v[154:157], v[200:203], v[24:27]
	v_mfma_f32_16x16x32_bf16 v[12:15], v[146:149], v[208:211], v[12:15]
	v_mfma_f32_16x16x32_bf16 v[8:11], v[154:157], v[208:211], v[8:11]
	s_setprio 0
	s_setprio 1
	v_mfma_f32_16x16x32_bf16 v[52:55], v[158:161], v[174:177], v[52:55]
	v_mfma_f32_16x16x32_bf16 v[48:51], v[166:169], v[174:177], v[48:51]
	v_mfma_f32_16x16x32_bf16 v[36:39], v[158:161], v[182:185], v[36:39]
	v_mfma_f32_16x16x32_bf16 v[32:35], v[166:169], v[182:185], v[32:35]
	v_mfma_f32_16x16x32_bf16 v[20:23], v[158:161], v[196:199], v[20:23]
	v_mfma_f32_16x16x32_bf16 v[16:19], v[166:169], v[196:199], v[16:19]
	v_mfma_f32_16x16x32_bf16 v[4:7], v[158:161], v[204:207], v[4:7]
	v_mfma_f32_16x16x32_bf16 v[0:3], v[166:169], v[204:207], v[0:3]
	v_mfma_f32_16x16x32_bf16 v[52:55], v[162:165], v[178:181], v[52:55]
	v_mfma_f32_16x16x32_bf16 v[48:51], v[170:173], v[178:181], v[48:51]
	v_mfma_f32_16x16x32_bf16 v[36:39], v[162:165], v[192:195], v[36:39]
	v_mfma_f32_16x16x32_bf16 v[32:35], v[170:173], v[192:195], v[32:35]
	v_mfma_f32_16x16x32_bf16 v[20:23], v[162:165], v[200:203], v[20:23]
	v_mfma_f32_16x16x32_bf16 v[16:19], v[170:173], v[200:203], v[16:19]
	v_mfma_f32_16x16x32_bf16 v[4:7], v[162:165], v[208:211], v[4:7]
	v_mfma_f32_16x16x32_bf16 v[0:3], v[170:173], v[208:211], v[0:3]
	s_setprio 0
	s_barrier
	s_add_i32 s43, s43, 2
	s_add_u32 s36, s36, 0x100
	s_addc_u32 s37, s37, 0
	s_add_u32 s33, s33, 0x100
	s_addc_u32 s42, s42, 0
	s_cmp_gt_u32 s43, 29
	s_cbranch_scc0 .LBB0_236
	s_branch .Lpeel_p2_done
	.p2align 6

;     __device__ __forceinline__ bool next(int i, Unit& u) const { return decode(i * G + c, u); }
; #define PG8_STAGE(bufoff, gbase, voff) do { _Pragma("unroll") for (int _i = 0; _i < 2; ++_i) \
;         __builtin_amdgcn_global_load_lds((const unsigned*)((const char*)(gbase) + (voff)[_i]), (LAS unsigned*)(lds + (bufoff) + ldsw + _i * 8192), 16, 0, 0); } while (0)
; #define PG8_LDA(dst, b, h) do { _Pragma("unroll") for (int m = 0; m < 4; ++m) _Pragma("unroll") for (int k = 0; k < 2; ++k) dst[m][k] = *(const LAS bf16x8*)(lds + PG8_SA(b, h) + aoff + m * 2048 + k * 1024); } while (0)
; #define PG8_LDB(dst, b, h) do { _Pragma("unroll") for (int n = 0; n < 2; ++n) _Pragma("unroll") for (int k = 0; k < 2; ++k) dst[n][k] = *(const LAS bf16x8*)(lds + PG8_SB(b, h) + boff + n * 2048 + k * 1024); } while (0)
; #define PG8_MMA(ai, bj, At, Bt) do { __builtin_amdgcn_s_setprio(1); _Pragma("unroll") for (int m = 0; m < 4; ++m) _Pragma("unroll") for (int n = 0; n < 2; ++n) _Pragma("unroll") for (int k = 0; k < 2; ++k) \
;         acc[ai][bj][m][n] = __builtin_amdgcn_mfma_f32_16x16x32_bf16(Bt[n][k], At[m][k], acc[ai][bj][m][n], 0, 0, 0); __builtin_amdgcn_s_setprio(0); } while (0)
; #define PG8_WAIT_V(n) asm volatile("s_waitcnt vmcnt(" #n ")" ::: "memory")
; #define PG8_WAIT_L(n) asm volatile("s_waitcnt lgkmcnt(" #n ")" ::: "memory")
; #define PG8_BAR __builtin_amdgcn_s_barrier()
; template <class Epi, class Sched, bool DEFER>
; __device__ __forceinline__ void gemm_fast_core(LAS unsigned char* lds, const GemmP g, const Sched& S, const Epi& E, f32x4 (&acc)[2][2][4][2], Unit& cur) {
;     ...
;         const bool has_next = S.next(ui + 1, nxt);
;         const char* nA = has_next ? (const char*)g.aptr(nxt) : cA; const char* nB = has_next ? (const char*)g.bptr(nxt) : cB;
;         for (int t = 0; t < nt; t += 2) {
;             const bool last = (t == nt - 2);
;             const char* a1 = cA + (size_t)(t + 1) * kstep;
;             const char* a2 = last ? nA : cA + (size_t)(t + 2) * kstep; const char* b2 = last ? nB : cB + (size_t)(t + 2) * kstep;
;             const char* a3 = a2 + kstep; const char* b3 = b2 + kstep;
;             PG8_LDB(B0, 0, 0); PG8_LDB(B1, 0, 1); PG8_SCHED; PG8_LDA(At, 0, 0); PG8_STAGE(PG8_SA(1, 1), a1 + hstepA, voffA);
;             PG8_WAIT_V(8); PG8_WAIT_L(0); PG8_BAR; PG8_MMA(0, 0, At, B0); PG8_MMA(0, 1, At, B1); PG8_BAR; PG8_SCHED;
.LBB0_1798:
	s_ashr_i32 s19, s18, 31
	s_lshl_b64 s[22:23], s[18:19], 20
	s_add_u32 s22, s90, s22
	s_addc_u32 s23, s91, s23
	s_and_b64 s[24:25], s[20:21], exec
	s_cselect_b32 s19, s23, s29
	s_cselect_b32 s47, s22, s28
	s_ashr_i32 s17, s16, 31
	s_lshl_b64 s[24:25], s[16:17], 20
	s_add_u32 s24, s96, s24
	s_addc_u32 s25, s97, s25
	s_and_b64 s[34:35], s[20:21], exec
	s_cselect_b32 s17, s25, s31
	s_cselect_b32 s48, s24, s30
	s_add_u32 s28, s28, 0x80080
	s_addc_u32 s29, s29, 0
	s_add_u32 s49, s30, 0x100
	s_addc_u32 s50, s31, 0
	s_mov_b32 s51, -2
	.p2align 6
	ds_read_b128 v[120:123], v205
	ds_read_b128 v[124:127], v205 offset:1024
	ds_read_b128 v[128:131], v205 offset:2048
	ds_read_b128 v[132:135], v205 offset:3072
	ds_read_b128 v[136:139], v206
	ds_read_b128 v[140:143], v206 offset:1024
	ds_read_b128 v[144:147], v206 offset:2048
	ds_read_b128 v[148:151], v206 offset:3072
	s_add_u32 s30, s28, 0xfff80080
	s_addc_u32 s31, s29, -1
	s_cmp_eq_u32 s51, 28
	s_cselect_b32 s35, s19, s31
	s_cselect_b32 s34, s47, s30
	s_cselect_b32 s31, s17, s50
	s_cselect_b32 s30, s48, s49
	v_lshl_add_u64 v[220:221], s[28:29], 0, v[164:165]
	s_add_i32 m0, s27, 0xc000
	ds_read_b128 v[168:171], v207
	ds_read_b128 v[172:175], v207 offset:1024
	ds_read_b128 v[176:179], v207 offset:2048
	ds_read_b128 v[180:183], v207 offset:3072
	ds_read_b128 v[184:187], v207 offset:4096
	ds_read_b128 v[208:211], v207 offset:5120
	ds_read_b128 v[212:215], v207 offset:6144
	ds_read_b128 v[216:219], v207 offset:7168
	global_load_lds_dwordx4 v[220:221], off
	v_lshl_add_u64 v[220:221], s[28:29], 0, v[166:167]
	s_add_i32 m0, s27, 0xe000
	s_nop 0
	global_load_lds_dwordx4 v[220:221], off
	s_cmp_eq_u32 s98, 0
	s_cbranch_scc1 .Lpw_p9_0_strict
	s_branch .Lpw_p9_0_done

; #define PG8_STAGE(bufoff, gbase, voff) do { _Pragma("unroll") for (int _i = 0; _i < 2; ++_i) \
;         __builtin_amdgcn_global_load_lds((const unsigned*)((const char*)(gbase) + (voff)[_i]), (LAS unsigned*)(lds + (bufoff) + ldsw + _i * 8192), 16, 0, 0); } while (0)
; #define PG8_LDA(dst, b, h) do { _Pragma("unroll") for (int m = 0; m < 4; ++m) _Pragma("unroll") for (int k = 0; k < 2; ++k) dst[m][k] = *(const LAS bf16x8*)(lds + PG8_SA(b, h) + aoff + m * 2048 + k * 1024); } while (0)
; #define PG8_LDB(dst, b, h) do { _Pragma("unroll") for (int n = 0; n < 2; ++n) _Pragma("unroll") for (int k = 0; k < 2; ++k) dst[n][k] = *(const LAS bf16x8*)(lds + PG8_SB(b, h) + boff + n * 2048 + k * 1024); } while (0)
; #define PG8_MMA(ai, bj, At, Bt) do { __builtin_amdgcn_s_setprio(1); _Pragma("unroll") for (int m = 0; m < 4; ++m) _Pragma("unroll") for (int n = 0; n < 2; ++n) _Pragma("unroll") for (int k = 0; k < 2; ++k) \
;         acc[ai][bj][m][n] = __builtin_amdgcn_mfma_f32_16x16x32_bf16(Bt[n][k], At[m][k], acc[ai][bj][m][n], 0, 0, 0); __builtin_amdgcn_s_setprio(0); } while (0)
; #define PG8_WAIT_V(n) asm volatile("s_waitcnt vmcnt(" #n ")" ::: "memory")
; #define PG8_WAIT_L(n) asm volatile("s_waitcnt lgkmcnt(" #n ")" ::: "memory")
; #define PG8_BAR __builtin_amdgcn_s_barrier()
; #define PG8_SCHED __builtin_amdgcn_sched_barrier(0)
; template <class Epi, class Sched, bool DEFER>
; __device__ __forceinline__ void gemm_fast_core(LAS unsigned char* lds, const GemmP g, const Sched& S, const Epi& E, f32x4 (&acc)[2][2][4][2], Unit& cur) {
;     ...
;             PG8_WAIT_V(8); PG8_WAIT_L(0); PG8_BAR; PG8_MMA(0, 0, At, B0); PG8_MMA(0, 1, At, B1); PG8_BAR; PG8_SCHED;
;             PG8_LDA(At, 0, 1); PG8_STAGE(PG8_SB(0, 0), b2, voffB); PG8_STAGE(PG8_SB(0, 1), b2 + hstepB, voffB); PG8_STAGE(PG8_SA(0, 0), a2, voffA);
;             PG8_WAIT_V(8); PG8_WAIT_L(0); PG8_BAR; PG8_MMA(1, 0, At, B0); PG8_MMA(1, 1, At, B1); PG8_BAR; PG8_SCHED;
;             PG8_LDB(B0, 1, 0); PG8_LDB(B1, 1, 1); PG8_SCHED; PG8_LDA(At, 1, 0); PG8_STAGE(PG8_SA(0, 1), a2 + hstepA, voffA);
.Lpw_p9_0_done:
	s_waitcnt lgkmcnt(0)
	s_barrier
	s_setprio 1
	s_waitcnt lgkmcnt(0)
	v_mfma_f32_16x16x32_bf16 v[156:159], v[120:123], v[168:171], 0
	v_mfma_f32_16x16x32_bf16 v[60:63], v[128:131], v[168:171], 0
	v_mfma_f32_16x16x32_bf16 v[116:119], v[120:123], v[176:179], 0
	v_mfma_f32_16x16x32_bf16 v[52:55], v[128:131], v[176:179], 0
	v_mfma_f32_16x16x32_bf16 v[108:111], v[120:123], v[184:187], 0
	v_mfma_f32_16x16x32_bf16 v[44:47], v[128:131], v[184:187], 0
	v_mfma_f32_16x16x32_bf16 v[100:103], v[120:123], v[212:215], 0
	v_mfma_f32_16x16x32_bf16 v[36:39], v[128:131], v[212:215], 0
	v_mfma_f32_16x16x32_bf16 v[156:159], v[124:127], v[172:175], v[156:159]
	v_mfma_f32_16x16x32_bf16 v[60:63], v[132:135], v[172:175], v[60:63]
	v_mfma_f32_16x16x32_bf16 v[116:119], v[124:127], v[180:183], v[116:119]
	v_mfma_f32_16x16x32_bf16 v[52:55], v[132:135], v[180:183], v[52:55]
	v_mfma_f32_16x16x32_bf16 v[108:111], v[124:127], v[208:211], v[108:111]
	v_mfma_f32_16x16x32_bf16 v[44:47], v[132:135], v[208:211], v[44:47]
	v_mfma_f32_16x16x32_bf16 v[100:103], v[124:127], v[216:219], v[100:103]
	v_mfma_f32_16x16x32_bf16 v[36:39], v[132:135], v[216:219], v[36:39]
	s_setprio 0
	s_setprio 1
	v_mfma_f32_16x16x32_bf16 v[152:155], v[136:139], v[168:171], 0
	v_mfma_f32_16x16x32_bf16 v[56:59], v[144:147], v[168:171], 0
	v_mfma_f32_16x16x32_bf16 v[112:115], v[136:139], v[176:179], 0
	v_mfma_f32_16x16x32_bf16 v[48:51], v[144:147], v[176:179], 0
	v_mfma_f32_16x16x32_bf16 v[104:107], v[136:139], v[184:187], 0
	v_mfma_f32_16x16x32_bf16 v[40:43], v[144:147], v[184:187], 0
	v_mfma_f32_16x16x32_bf16 v[96:99], v[136:139], v[212:215], 0
	v_mfma_f32_16x16x32_bf16 v[32:35], v[144:147], v[212:215], 0
	v_mfma_f32_16x16x32_bf16 v[152:155], v[140:143], v[172:175], v[152:155]
	v_mfma_f32_16x16x32_bf16 v[56:59], v[148:151], v[172:175], v[56:59]
	v_mfma_f32_16x16x32_bf16 v[112:115], v[140:143], v[180:183], v[112:115]
	v_mfma_f32_16x16x32_bf16 v[48:51], v[148:151], v[180:183], v[48:51]
	v_mfma_f32_16x16x32_bf16 v[104:107], v[140:143], v[208:211], v[104:107]
	v_mfma_f32_16x16x32_bf16 v[40:43], v[148:151], v[208:211], v[40:43]
	v_mfma_f32_16x16x32_bf16 v[96:99], v[140:143], v[216:219], v[96:99]
	v_mfma_f32_16x16x32_bf16 v[32:35], v[148:151], v[216:219], v[32:35]
	s_setprio 0
	s_barrier
	s_add_i32 s52, s44, s36
	v_lshl_add_u64 v[220:221], s[30:31], 0, v[162:163]
	s_mov_b32 m0, s52
	ds_read_b128 v[168:171], v207 offset:16384
	ds_read_b128 v[172:175], v207 offset:17408
	ds_read_b128 v[176:179], v207 offset:18432
	ds_read_b128 v[180:183], v207 offset:19456
	ds_read_b128 v[184:187], v207 offset:20480
	ds_read_b128 v[208:211], v207 offset:21504
	ds_read_b128 v[212:215], v207 offset:22528
	ds_read_b128 v[216:219], v207 offset:23552
	global_load_lds_dwordx4 v[220:221], off
	s_add_i32 m0, s52, 0x2000
	s_add_u32 s52, s30, 0x80000
	v_lshl_add_u64 v[222:223], s[30:31], 0, v[160:161]
	s_addc_u32 s53, s31, 0
	s_add_i32 s54, s45, s36
	global_load_lds_dwordx4 v[222:223], off
	v_lshl_add_u64 v[224:225], s[52:53], 0, v[162:163]
	s_mov_b32 m0, s54
	v_lshl_add_u64 v[226:227], s[34:35], 0, v[192:193]
	global_load_lds_dwordx4 v[224:225], off
	v_lshl_add_u64 v[224:225], s[52:53], 0, v[160:161]
	s_add_i32 m0, s54, 0x2000
	s_nop 0
	global_load_lds_dwordx4 v[224:225], off
	v_lshl_add_u64 v[224:225], s[34:35], 0, v[190:191]
	s_mov_b32 m0, s27
	s_nop 0
	global_load_lds_dwordx4 v[224:225], off
	s_mov_b32 m0, s38
	s_nop 0
	global_load_lds_dwordx4 v[226:227], off
	s_cmp_eq_u32 s98, 0
	s_cbranch_scc1 .Lpw_p9_1_strict
	s_branch .Lpw_p9_1_done

; #define PG8_STAGE(bufoff, gbase, voff) do { _Pragma("unroll") for (int _i = 0; _i < 2; ++_i) \
;         __builtin_amdgcn_global_load_lds((const unsigned*)((const char*)(gbase) + (voff)[_i]), (LAS unsigned*)(lds + (bufoff) + ldsw + _i * 8192), 16, 0, 0); } while (0)
; #define PG8_LDA(dst, b, h) do { _Pragma("unroll") for (int m = 0; m < 4; ++m) _Pragma("unroll") for (int k = 0; k < 2; ++k) dst[m][k] = *(const LAS bf16x8*)(lds + PG8_SA(b, h) + aoff + m * 2048 + k * 1024); } while (0)
; #define PG8_LDB(dst, b, h) do { _Pragma("unroll") for (int n = 0; n < 2; ++n) _Pragma("unroll") for (int k = 0; k < 2; ++k) dst[n][k] = *(const LAS bf16x8*)(lds + PG8_SB(b, h) + boff + n * 2048 + k * 1024); } while (0)
; #define PG8_MMA(ai, bj, At, Bt) do { __builtin_amdgcn_s_setprio(1); _Pragma("unroll") for (int m = 0; m < 4; ++m) _Pragma("unroll") for (int n = 0; n < 2; ++n) _Pragma("unroll") for (int k = 0; k < 2; ++k) \
;         acc[ai][bj][m][n] = __builtin_amdgcn_mfma_f32_16x16x32_bf16(Bt[n][k], At[m][k], acc[ai][bj][m][n], 0, 0, 0); __builtin_amdgcn_s_setprio(0); } while (0)
; #define PG8_WAIT_V(n) asm volatile("s_waitcnt vmcnt(" #n ")" ::: "memory")
; #define PG8_WAIT_L(n) asm volatile("s_waitcnt lgkmcnt(" #n ")" ::: "memory")
; #define PG8_BAR __builtin_amdgcn_s_barrier()
; #define PG8_SCHED __builtin_amdgcn_sched_barrier(0)
; template <class Epi, class Sched, bool DEFER>
; __device__ __forceinline__ void gemm_fast_core(LAS unsigned char* lds, const GemmP g, const Sched& S, const Epi& E, f32x4 (&acc)[2][2][4][2], Unit& cur) {
;     ...
;             PG8_WAIT_V(8); PG8_WAIT_L(0); PG8_BAR; PG8_MMA(1, 0, At, B0); PG8_MMA(1, 1, At, B1); PG8_BAR; PG8_SCHED;
;             PG8_LDB(B0, 1, 0); PG8_LDB(B1, 1, 1); PG8_SCHED; PG8_LDA(At, 1, 0); PG8_STAGE(PG8_SA(0, 1), a2 + hstepA, voffA);
.Lpw_p9_1_done:
	s_waitcnt lgkmcnt(0)
	s_barrier
	s_setprio 1
	s_waitcnt lgkmcnt(0)
	v_mfma_f32_16x16x32_bf16 v[92:95], v[120:123], v[168:171], 0
	v_mfma_f32_16x16x32_bf16 v[28:31], v[128:131], v[168:171], 0
	v_mfma_f32_16x16x32_bf16 v[84:87], v[120:123], v[176:179], 0
	v_mfma_f32_16x16x32_bf16 v[20:23], v[128:131], v[176:179], 0
	v_mfma_f32_16x16x32_bf16 v[76:79], v[120:123], v[184:187], 0
	v_mfma_f32_16x16x32_bf16 v[12:15], v[128:131], v[184:187], 0
	v_mfma_f32_16x16x32_bf16 v[68:71], v[120:123], v[212:215], 0
	v_mfma_f32_16x16x32_bf16 v[4:7], v[128:131], v[212:215], 0
	v_mfma_f32_16x16x32_bf16 v[92:95], v[124:127], v[172:175], v[92:95]
	v_mfma_f32_16x16x32_bf16 v[28:31], v[132:135], v[172:175], v[28:31]
	v_mfma_f32_16x16x32_bf16 v[84:87], v[124:127], v[180:183], v[84:87]
	v_mfma_f32_16x16x32_bf16 v[20:23], v[132:135], v[180:183], v[20:23]
	v_mfma_f32_16x16x32_bf16 v[76:79], v[124:127], v[208:211], v[76:79]
	v_mfma_f32_16x16x32_bf16 v[12:15], v[132:135], v[208:211], v[12:15]
	v_mfma_f32_16x16x32_bf16 v[68:71], v[124:127], v[216:219], v[68:71]
	v_mfma_f32_16x16x32_bf16 v[4:7], v[132:135], v[216:219], v[4:7]
	s_setprio 0
	s_setprio 1
	v_mfma_f32_16x16x32_bf16 v[88:91], v[136:139], v[168:171], 0
	v_mfma_f32_16x16x32_bf16 v[24:27], v[144:147], v[168:171], 0
	v_mfma_f32_16x16x32_bf16 v[80:83], v[136:139], v[176:179], 0
	v_mfma_f32_16x16x32_bf16 v[16:19], v[144:147], v[176:179], 0
	v_mfma_f32_16x16x32_bf16 v[72:75], v[136:139], v[184:187], 0
	v_mfma_f32_16x16x32_bf16 v[8:11], v[144:147], v[184:187], 0
	v_mfma_f32_16x16x32_bf16 v[64:67], v[136:139], v[212:215], 0
	v_mfma_f32_16x16x32_bf16 v[0:3], v[144:147], v[212:215], 0
	v_mfma_f32_16x16x32_bf16 v[88:91], v[140:143], v[172:175], v[88:91]
	v_mfma_f32_16x16x32_bf16 v[24:27], v[148:151], v[172:175], v[24:27]
	v_mfma_f32_16x16x32_bf16 v[80:83], v[140:143], v[180:183], v[80:83]
	v_mfma_f32_16x16x32_bf16 v[16:19], v[148:151], v[180:183], v[16:19]
	v_mfma_f32_16x16x32_bf16 v[72:75], v[140:143], v[208:211], v[72:75]
	v_mfma_f32_16x16x32_bf16 v[8:11], v[148:151], v[208:211], v[8:11]
	v_mfma_f32_16x16x32_bf16 v[64:67], v[140:143], v[216:219], v[64:67]
	v_mfma_f32_16x16x32_bf16 v[0:3], v[148:151], v[216:219], v[0:3]
	s_setprio 0
	s_barrier
	s_add_i32 s52, 0, 0x18000
	s_add_i32 s53, 0, 0x1c000
	v_add_u32_e32 v132, s52, v196
	v_add_u32_e32 v148, s53, v196
	ds_read_b128 v[120:123], v132
	ds_read_b128 v[124:127], v132 offset:1024
	ds_read_b128 v[128:131], v132 offset:2048
	ds_read_b128 v[132:135], v132 offset:3072
	ds_read_b128 v[136:139], v148
	ds_read_b128 v[140:143], v148 offset:1024
	ds_read_b128 v[144:147], v148 offset:2048
	ds_read_b128 v[148:151], v148 offset:3072
	s_add_u32 s34, s34, 0x80000
	s_addc_u32 s35, s35, 0
	s_mov_b32 m0, s39
	v_lshl_add_u64 v[228:229], s[34:35], 0, v[190:191]
	ds_read_b128 v[168:171], v207 offset:32768
	ds_read_b128 v[172:175], v207 offset:33792
	ds_read_b128 v[176:179], v207 offset:34816
	ds_read_b128 v[180:183], v207 offset:35840
	ds_read_b128 v[184:187], v207 offset:36864
	ds_read_b128 v[208:211], v207 offset:37888
	ds_read_b128 v[212:215], v207 offset:38912
	ds_read_b128 v[216:219], v207 offset:39936
	global_load_lds_dwordx4 v[228:229], off
	v_lshl_add_u64 v[228:229], s[34:35], 0, v[192:193]
	s_mov_b32 m0, s40
	s_nop 0
	global_load_lds_dwordx4 v[228:229], off
	s_cmp_eq_u32 s98, 0
	s_cbranch_scc1 .Lpw_p9_2_strict
	s_branch .Lpw_p9_2_done

; #define PG8_STAGE(bufoff, gbase, voff) do { _Pragma("unroll") for (int _i = 0; _i < 2; ++_i) \
;         __builtin_amdgcn_global_load_lds((const unsigned*)((const char*)(gbase) + (voff)[_i]), (LAS unsigned*)(lds + (bufoff) + ldsw + _i * 8192), 16, 0, 0); } while (0)
; #define PG8_LDA(dst, b, h) do { _Pragma("unroll") for (int m = 0; m < 4; ++m) _Pragma("unroll") for (int k = 0; k < 2; ++k) dst[m][k] = *(const LAS bf16x8*)(lds + PG8_SA(b, h) + aoff + m * 2048 + k * 1024); } while (0)
; #define PG8_LDB(dst, b, h) do { _Pragma("unroll") for (int n = 0; n < 2; ++n) _Pragma("unroll") for (int k = 0; k < 2; ++k) dst[n][k] = *(const LAS bf16x8*)(lds + PG8_SB(b, h) + boff + n * 2048 + k * 1024); } while (0)
; #define PG8_MMA(ai, bj, At, Bt) do { __builtin_amdgcn_s_setprio(1); _Pragma("unroll") for (int m = 0; m < 4; ++m) _Pragma("unroll") for (int n = 0; n < 2; ++n) _Pragma("unroll") for (int k = 0; k < 2; ++k) \
;         acc[ai][bj][m][n] = __builtin_amdgcn_mfma_f32_16x16x32_bf16(Bt[n][k], At[m][k], acc[ai][bj][m][n], 0, 0, 0); __builtin_amdgcn_s_setprio(0); } while (0)
; #define PG8_WAIT_V(n) asm volatile("s_waitcnt vmcnt(" #n ")" ::: "memory")
; #define PG8_WAIT_L(n) asm volatile("s_waitcnt lgkmcnt(" #n ")" ::: "memory")
; #define PG8_BAR __builtin_amdgcn_s_barrier()
; #define PG8_SCHED __builtin_amdgcn_sched_barrier(0)
; template <class Epi, class Sched, bool DEFER>
; __device__ __forceinline__ void gemm_fast_core(LAS unsigned char* lds, const GemmP g, const Sched& S, const Epi& E, f32x4 (&acc)[2][2][4][2], Unit& cur) {
;     ...
;             PG8_LDB(B0, 1, 0); PG8_LDB(B1, 1, 1); PG8_SCHED; PG8_LDA(At, 1, 0); PG8_STAGE(PG8_SA(0, 1), a2 + hstepA, voffA);
;             PG8_WAIT_V(8); PG8_WAIT_L(0); PG8_BAR; PG8_MMA(0, 0, At, B0); PG8_MMA(0, 1, At, B1); PG8_BAR; PG8_SCHED;
;             PG8_LDA(At, 1, 1); PG8_STAGE(PG8_SB(1, 0), b3, voffB); PG8_STAGE(PG8_SB(1, 1), b3 + hstepB, voffB); PG8_STAGE(PG8_SA(1, 0), a3, voffA);
;             PG8_WAIT_V(8); PG8_WAIT_L(0); PG8_BAR; PG8_MMA(1, 0, At, B0); PG8_MMA(1, 1, At, B1); PG8_BAR; PG8_SCHED;
.Lpw_p9_2_done:
	s_waitcnt lgkmcnt(0)
	s_barrier
	s_setprio 1
	s_waitcnt lgkmcnt(0)
	v_mfma_f32_16x16x32_bf16 v[156:159], v[120:123], v[168:171], v[156:159]
	v_mfma_f32_16x16x32_bf16 v[60:63], v[128:131], v[168:171], v[60:63]
	v_mfma_f32_16x16x32_bf16 v[116:119], v[120:123], v[176:179], v[116:119]
	v_mfma_f32_16x16x32_bf16 v[52:55], v[128:131], v[176:179], v[52:55]
	v_mfma_f32_16x16x32_bf16 v[108:111], v[120:123], v[184:187], v[108:111]
	v_mfma_f32_16x16x32_bf16 v[44:47], v[128:131], v[184:187], v[44:47]
	v_mfma_f32_16x16x32_bf16 v[100:103], v[120:123], v[212:215], v[100:103]
	v_mfma_f32_16x16x32_bf16 v[36:39], v[128:131], v[212:215], v[36:39]
	v_mfma_f32_16x16x32_bf16 v[156:159], v[124:127], v[172:175], v[156:159]
	v_mfma_f32_16x16x32_bf16 v[60:63], v[132:135], v[172:175], v[60:63]
	v_mfma_f32_16x16x32_bf16 v[116:119], v[124:127], v[180:183], v[116:119]
	v_mfma_f32_16x16x32_bf16 v[52:55], v[132:135], v[180:183], v[52:55]
	v_mfma_f32_16x16x32_bf16 v[108:111], v[124:127], v[208:211], v[108:111]
	v_mfma_f32_16x16x32_bf16 v[44:47], v[132:135], v[208:211], v[44:47]
	v_mfma_f32_16x16x32_bf16 v[100:103], v[124:127], v[216:219], v[100:103]
	v_mfma_f32_16x16x32_bf16 v[36:39], v[132:135], v[216:219], v[36:39]
	s_setprio 0
	s_setprio 1
	v_mfma_f32_16x16x32_bf16 v[152:155], v[136:139], v[168:171], v[152:155]
	v_mfma_f32_16x16x32_bf16 v[56:59], v[144:147], v[168:171], v[56:59]
	v_mfma_f32_16x16x32_bf16 v[112:115], v[136:139], v[176:179], v[112:115]
	v_mfma_f32_16x16x32_bf16 v[48:51], v[144:147], v[176:179], v[48:51]
	v_mfma_f32_16x16x32_bf16 v[104:107], v[136:139], v[184:187], v[104:107]
	v_mfma_f32_16x16x32_bf16 v[40:43], v[144:147], v[184:187], v[40:43]
	v_mfma_f32_16x16x32_bf16 v[96:99], v[136:139], v[212:215], v[96:99]
	v_mfma_f32_16x16x32_bf16 v[32:35], v[144:147], v[212:215], v[32:35]
	v_mfma_f32_16x16x32_bf16 v[152:155], v[140:143], v[172:175], v[152:155]
	v_mfma_f32_16x16x32_bf16 v[56:59], v[148:151], v[172:175], v[56:59]
	v_mfma_f32_16x16x32_bf16 v[112:115], v[140:143], v[180:183], v[112:115]
	v_mfma_f32_16x16x32_bf16 v[48:51], v[148:151], v[180:183], v[48:51]
	v_mfma_f32_16x16x32_bf16 v[104:107], v[140:143], v[208:211], v[104:107]
	v_mfma_f32_16x16x32_bf16 v[40:43], v[148:151], v[208:211], v[40:43]
	v_mfma_f32_16x16x32_bf16 v[96:99], v[140:143], v[216:219], v[96:99]
	v_mfma_f32_16x16x32_bf16 v[32:35], v[148:151], v[216:219], v[32:35]
	s_setprio 0
	s_barrier
	s_add_i32 s34, s52, s36
	v_lshl_add_u64 v[220:221], v[220:221], 0, s[8:9]
	s_mov_b32 m0, s34
	ds_read_b128 v[168:171], v207 offset:49152
	ds_read_b128 v[172:175], v207 offset:50176
	ds_read_b128 v[176:179], v207 offset:51200
	ds_read_b128 v[180:183], v207 offset:52224
	ds_read_b128 v[184:187], v207 offset:53248
	ds_read_b128 v[208:211], v207 offset:54272
	ds_read_b128 v[212:215], v207 offset:55296
	ds_read_b128 v[216:219], v207 offset:56320
	global_load_lds_dwordx4 v[220:221], off
	s_add_i32 m0, s34, 0x2000
	s_add_u32 s30, s30, 0x80080
	v_lshl_add_u64 v[220:221], v[222:223], 0, s[8:9]
	s_addc_u32 s31, s31, 0
	s_add_i32 s34, s53, s36
	global_load_lds_dwordx4 v[220:221], off
	v_lshl_add_u64 v[220:221], s[30:31], 0, v[162:163]
	s_mov_b32 m0, s34
	s_nop 0
	global_load_lds_dwordx4 v[220:221], off
	v_lshl_add_u64 v[220:221], s[30:31], 0, v[160:161]
	s_add_i32 m0, s34, 0x2000
	s_nop 0
	global_load_lds_dwordx4 v[220:221], off
	v_lshl_add_u64 v[220:221], v[224:225], 0, s[8:9]
	s_mov_b32 m0, s42
	s_nop 0
	global_load_lds_dwordx4 v[220:221], off
	v_lshl_add_u64 v[220:221], v[226:227], 0, s[8:9]
	s_mov_b32 m0, s43
	s_nop 0
	global_load_lds_dwordx4 v[220:221], off
	s_waitcnt vmcnt(8)
	s_waitcnt lgkmcnt(0)
	s_barrier
	s_setprio 1
	s_waitcnt lgkmcnt(0)
	v_mfma_f32_16x16x32_bf16 v[92:95], v[120:123], v[168:171], v[92:95]
	v_mfma_f32_16x16x32_bf16 v[28:31], v[128:131], v[168:171], v[28:31]
	v_mfma_f32_16x16x32_bf16 v[84:87], v[120:123], v[176:179], v[84:87]
	v_mfma_f32_16x16x32_bf16 v[20:23], v[128:131], v[176:179], v[20:23]
	v_mfma_f32_16x16x32_bf16 v[76:79], v[120:123], v[184:187], v[76:79]
	v_mfma_f32_16x16x32_bf16 v[12:15], v[128:131], v[184:187], v[12:15]
	v_mfma_f32_16x16x32_bf16 v[68:71], v[120:123], v[212:215], v[68:71]
	v_mfma_f32_16x16x32_bf16 v[4:7], v[128:131], v[212:215], v[4:7]
	v_mfma_f32_16x16x32_bf16 v[92:95], v[124:127], v[172:175], v[92:95]
	v_mfma_f32_16x16x32_bf16 v[28:31], v[132:135], v[172:175], v[28:31]
	v_mfma_f32_16x16x32_bf16 v[84:87], v[124:127], v[180:183], v[84:87]
	v_mfma_f32_16x16x32_bf16 v[20:23], v[132:135], v[180:183], v[20:23]
	v_mfma_f32_16x16x32_bf16 v[76:79], v[124:127], v[208:211], v[76:79]
	v_mfma_f32_16x16x32_bf16 v[12:15], v[132:135], v[208:211], v[12:15]
	v_mfma_f32_16x16x32_bf16 v[68:71], v[124:127], v[216:219], v[68:71]
	v_mfma_f32_16x16x32_bf16 v[4:7], v[132:135], v[216:219], v[4:7]
	s_setprio 0
	s_setprio 1
	v_mfma_f32_16x16x32_bf16 v[88:91], v[136:139], v[168:171], v[88:91]
	v_mfma_f32_16x16x32_bf16 v[24:27], v[144:147], v[168:171], v[24:27]
	v_mfma_f32_16x16x32_bf16 v[80:83], v[136:139], v[176:179], v[80:83]
	v_mfma_f32_16x16x32_bf16 v[16:19], v[144:147], v[176:179], v[16:19]
	v_mfma_f32_16x16x32_bf16 v[72:75], v[136:139], v[184:187], v[72:75]
	v_mfma_f32_16x16x32_bf16 v[8:11], v[144:147], v[184:187], v[8:11]
	v_mfma_f32_16x16x32_bf16 v[64:67], v[136:139], v[212:215], v[64:67]
	v_mfma_f32_16x16x32_bf16 v[0:3], v[144:147], v[212:215], v[0:3]
	v_mfma_f32_16x16x32_bf16 v[88:91], v[140:143], v[172:175], v[88:91]
	v_mfma_f32_16x16x32_bf16 v[24:27], v[148:151], v[172:175], v[24:27]
	v_mfma_f32_16x16x32_bf16 v[80:83], v[140:143], v[180:183], v[80:83]
	v_mfma_f32_16x16x32_bf16 v[16:19], v[148:151], v[180:183], v[16:19]
	v_mfma_f32_16x16x32_bf16 v[72:75], v[140:143], v[208:211], v[72:75]
	v_mfma_f32_16x16x32_bf16 v[8:11], v[148:151], v[208:211], v[8:11]
	v_mfma_f32_16x16x32_bf16 v[64:67], v[140:143], v[216:219], v[64:67]
	v_mfma_f32_16x16x32_bf16 v[0:3], v[148:151], v[216:219], v[0:3]
	s_setprio 0
	s_barrier
	s_add_i32 s51, s51, 2
	s_add_u32 s28, s28, 0x100
	s_addc_u32 s29, s29, 0
	s_add_u32 s49, s49, 0x100
	s_addc_u32 s50, s50, 0
	s_cmp_gt_u32 s51, 29
	s_cbranch_scc0 .LBB0_1799
	s_branch .Lpeel_p9_done
	.p2align 6
